# HG logf: removed provably-dead denormal/inf branches; hoisted stage-a LDS reads
# baseline (speedup 1.0000x reference)
; #define LAS __attribute__((address_space(3)))
; DI float bf2f(unsigned short h) { return __uint_as_float((unsigned)h << 16); }
; DI void hg_unit(LAS unsigned char* lds, const MixL& P, int pi) {
;     ...
;         float qv[16], kv[16], cs[16]; unsigned vv[8]; float runs = 0.f;
; #pragma unroll
;         for (int i = 0; i < 16; ++i) { const LAS unsigned char* sp = lds + HG_STG + (i & 1) * 8192 + (chain * 256 + (8 * tq + (i >> 1)) * 8 + (d >> 3)) * 16 + (d & 7) * 2;
;             const float a = bf2f(*(const LAS unsigned short*)(sp + 2 * 8192)), qr = bf2f(*(const LAS unsigned short*)sp); const unsigned vb = *(const LAS unsigned short*)(sp + 4 * 8192);
;             if (i & 1) vv[i >> 1] |= vb << 16; else vv[i >> 1] = vb;
;             const float e = fminf(__expf(-a), 1e30f), sg = __builtin_amdgcn_rcpf(1.0f + e);
;             const float f = lb + oml * sg;
;             runs += __logf(f); cs[i] = runs; qv[i] = qr; kv[i] = oml * (e * sg); }
;         CUMQ[tq * 64 + d] = runs;
.LBB0_524:
	s_waitcnt vmcnt(0)
	s_waitcnt lgkmcnt(0)
	s_barrier
	ds_read_u16 v210, v130 offset:16384
	ds_read_u16 v211, v144 offset:32768
	ds_read_u16 v212, v130 offset:32768
	ds_read_u16 v213, v131 offset:16384
	ds_read_u16 v214, v131 offset:32768
	ds_read_u16 v215, v132 offset:16384
	ds_read_u16 v216, v132 offset:32768
	ds_read_u16 v217, v133 offset:16384
	ds_read_u16 v218, v133 offset:32768
	ds_read_u16 v219, v134 offset:16384
	ds_read_u16 v220, v134 offset:32768
	ds_read_u16 v221, v135 offset:16384
	ds_read_u16 v222, v135 offset:32768
	ds_read_u16 v223, v136 offset:16384
	ds_read_u16 v224, v136 offset:32768
	ds_read_u16 v225, v137 offset:16384
	ds_read_u16 v226, v137 offset:32768
	ds_read_u16 v227, v138 offset:16384
	ds_read_u16 v228, v138 offset:32768
	ds_read_u16 v229, v139 offset:16384
	ds_read_u16 v230, v139 offset:32768
	ds_read_u16 v231, v140 offset:16384
	ds_read_u16 v232, v140 offset:32768
	ds_read_u16 v233, v141 offset:16384
	ds_read_u16 v234, v141 offset:32768
	ds_read_u16 v235, v142 offset:16384
	ds_read_u16 v236, v142 offset:32768
	ds_read_u16 v237, v143 offset:16384
	ds_read_u16 v238, v143 offset:32768
	ds_read_u16 v239, v144 offset:16384
	ds_read_u16 v240, v145 offset:16384
	ds_read_u16 v241, v145 offset:32768
	s_waitcnt lgkmcnt(0)
	v_mov_b32_e32 v4, v210
	v_mov_b32_e32 v19, v211
	v_mov_b32_e32 v5, v212
	s_waitcnt lgkmcnt(2)
	v_lshlrev_b32_e32 v4, 16, v4
	v_mul_f32_e32 v4, 0xbfb8aa3b, v4
	v_exp_f32_e32 v4, v4
	s_nop 0
	v_min_f32_e32 v14, 0x7149f2ca, v4
	v_add_f32_e32 v4, 1.0, v14
	v_rcp_f32_e32 v16, v4
	s_nop 0
	v_fma_f32 v4, v90, v16, v122
	v_log_f32_e32 v4, v4
	s_nop 0
	v_mul_f32_e32 v6, 0x3f317217, v4
	v_fma_f32 v6, v4, s95, -v6
	v_fmac_f32_e32 v6, 0x3377d1cf, v4
	v_fmac_f32_e32 v6, 0x3f317217, v4
	v_mov_b32_e32 v4, v6
	v_add_f32_e32 v9, 0, v4
	v_mov_b32_e32 v4, v213
	s_waitcnt lgkmcnt(0)
	v_lshlrev_b32_e32 v6, 16, v4
	v_mov_b32_e32 v4, v214
	s_waitcnt lgkmcnt(0)
	v_lshl_or_b32 v4, v4, 16, v5
	v_mul_f32_e32 v5, 0xbfb8aa3b, v6
	v_exp_f32_e32 v5, v5
	s_nop 0
	v_min_f32_e32 v15, 0x7149f2ca, v5
	v_add_f32_e32 v5, 1.0, v15
	v_rcp_f32_e32 v17, v5
	s_nop 0
	v_fma_f32 v5, v90, v17, v122
	v_pk_mul_f32 v[14:15], v[14:15], v[16:17]
	v_log_f32_e32 v5, v5
	v_pk_mul_f32 v[14:15], v[90:91], v[14:15]
	v_mul_f32_e32 v6, 0x3f317217, v5
	v_fma_f32 v6, v5, s95, -v6
	v_fmac_f32_e32 v6, 0x3377d1cf, v5
	v_fmac_f32_e32 v6, 0x3f317217, v5
	v_mov_b32_e32 v5, v6
	v_add_f32_e32 v48, v9, v5
	v_mov_b32_e32 v5, v215
	v_mov_b32_e32 v6, v216
	s_waitcnt lgkmcnt(1)
	v_lshlrev_b32_e32 v5, 16, v5
	v_mul_f32_e32 v5, 0xbfb8aa3b, v5
	v_exp_f32_e32 v5, v5
	s_nop 0
	v_min_f32_e32 v42, 0x7149f2ca, v5
	v_add_f32_e32 v5, 1.0, v42
	v_rcp_f32_e32 v44, v5
	s_nop 0
	v_fma_f32 v5, v90, v44, v122
	v_log_f32_e32 v5, v5
	s_nop 0
	v_mul_f32_e32 v7, 0x3f317217, v5
	v_fma_f32 v7, v5, s95, -v7
	v_fmac_f32_e32 v7, 0x3377d1cf, v5
	v_fmac_f32_e32 v7, 0x3f317217, v5
	v_mov_b32_e32 v5, v7
	v_add_f32_e32 v58, v48, v5
	v_mov_b32_e32 v5, v217
	s_waitcnt lgkmcnt(0)
	v_lshlrev_b32_e32 v7, 16, v5
	v_mov_b32_e32 v5, v218
	s_waitcnt lgkmcnt(0)
	v_lshl_or_b32 v5, v5, 16, v6
	v_mul_f32_e32 v6, 0xbfb8aa3b, v7
	v_exp_f32_e32 v6, v6
	s_nop 0
	v_min_f32_e32 v43, 0x7149f2ca, v6
	v_add_f32_e32 v6, 1.0, v43
	v_rcp_f32_e32 v45, v6
	s_nop 0
	v_fma_f32 v6, v90, v45, v122
	v_pk_mul_f32 v[42:43], v[42:43], v[44:45]
	v_log_f32_e32 v6, v6
	v_pk_mul_f32 v[42:43], v[90:91], v[42:43]
	v_mul_f32_e32 v7, 0x3f317217, v6
	v_fma_f32 v7, v6, s95, -v7
	v_fmac_f32_e32 v7, 0x3377d1cf, v6
	v_fmac_f32_e32 v7, 0x3f317217, v6
	v_mov_b32_e32 v6, v7
	v_add_f32_e32 v62, v58, v6
	v_mov_b32_e32 v6, v219
	v_mov_b32_e32 v7, v220
	s_waitcnt lgkmcnt(1)
	v_lshlrev_b32_e32 v6, 16, v6
	v_mul_f32_e32 v6, 0xbfb8aa3b, v6
	v_exp_f32_e32 v6, v6
	s_nop 0
	v_min_f32_e32 v38, 0x7149f2ca, v6
	v_add_f32_e32 v6, 1.0, v38
	v_rcp_f32_e32 v40, v6
	s_nop 0
	v_fma_f32 v6, v90, v40, v122
	v_log_f32_e32 v6, v6
	s_nop 0
	v_mul_f32_e32 v10, 0x3f317217, v6
	v_fma_f32 v10, v6, s95, -v10
	v_fmac_f32_e32 v10, 0x3377d1cf, v6
	v_fmac_f32_e32 v10, 0x3f317217, v6
	v_mov_b32_e32 v6, v10
	v_add_f32_e32 v56, v62, v6
	v_mov_b32_e32 v6, v221
	s_waitcnt lgkmcnt(0)
	v_lshlrev_b32_e32 v10, 16, v6
	v_mov_b32_e32 v6, v222
	s_waitcnt lgkmcnt(0)
	v_lshl_or_b32 v6, v6, 16, v7
	v_mul_f32_e32 v7, 0xbfb8aa3b, v10
	v_exp_f32_e32 v7, v7
	s_nop 0
	v_min_f32_e32 v39, 0x7149f2ca, v7
	v_add_f32_e32 v7, 1.0, v39
	v_rcp_f32_e32 v41, v7
	s_nop 0
	v_fma_f32 v7, v90, v41, v122
	v_pk_mul_f32 v[38:39], v[38:39], v[40:41]
	v_log_f32_e32 v7, v7
	v_pk_mul_f32 v[38:39], v[90:91], v[38:39]
	v_mul_f32_e32 v10, 0x3f317217, v7
	v_fma_f32 v10, v7, s95, -v10
	v_fmac_f32_e32 v10, 0x3377d1cf, v7
	v_fmac_f32_e32 v10, 0x3f317217, v7
	v_mov_b32_e32 v7, v10
	v_add_f32_e32 v61, v56, v7
	v_mov_b32_e32 v7, v223
	v_mov_b32_e32 v10, v224
	s_waitcnt lgkmcnt(1)
	v_lshlrev_b32_e32 v7, 16, v7
	v_mul_f32_e32 v7, 0xbfb8aa3b, v7
	v_exp_f32_e32 v7, v7
	s_nop 0
	v_min_f32_e32 v34, 0x7149f2ca, v7
	v_add_f32_e32 v7, 1.0, v34
	v_rcp_f32_e32 v36, v7
	s_nop 0
	v_fma_f32 v7, v90, v36, v122
	v_log_f32_e32 v7, v7
	s_nop 0
	v_mul_f32_e32 v11, 0x3f317217, v7
	v_fma_f32 v11, v7, s95, -v11
	v_fmac_f32_e32 v11, 0x3377d1cf, v7
	v_fmac_f32_e32 v11, 0x3f317217, v7
	v_mov_b32_e32 v7, v11
	v_add_f32_e32 v54, v61, v7
	v_mov_b32_e32 v7, v225
	s_waitcnt lgkmcnt(0)
	v_lshlrev_b32_e32 v11, 16, v7
	v_mov_b32_e32 v7, v226
	s_waitcnt lgkmcnt(0)
; #define LAS __attribute__((address_space(3)))
; DI float bf2f(unsigned short h) { return __uint_as_float((unsigned)h << 16); }
; DI void hg_unit(LAS unsigned char* lds, const MixL& P, int pi) {
;     ...
;         float qv[16], kv[16], cs[16]; unsigned vv[8]; float runs = 0.f;
; #pragma unroll
;         for (int i = 0; i < 16; ++i) { const LAS unsigned char* sp = lds + HG_STG + (i & 1) * 8192 + (chain * 256 + (8 * tq + (i >> 1)) * 8 + (d >> 3)) * 16 + (d & 7) * 2;
;             const float a = bf2f(*(const LAS unsigned short*)(sp + 2 * 8192)), qr = bf2f(*(const LAS unsigned short*)sp); const unsigned vb = *(const LAS unsigned short*)(sp + 4 * 8192);
;             if (i & 1) vv[i >> 1] |= vb << 16; else vv[i >> 1] = vb;
;             const float e = fminf(__expf(-a), 1e30f), sg = __builtin_amdgcn_rcpf(1.0f + e);
;             const float f = lb + oml * sg;
;             runs += __logf(f); cs[i] = runs; qv[i] = qr; kv[i] = oml * (e * sg); }
;         CUMQ[tq * 64 + d] = runs;
;         __syncthreads();
	v_lshl_or_b32 v7, v7, 16, v10
	v_mul_f32_e32 v10, 0xbfb8aa3b, v11
	v_exp_f32_e32 v10, v10
	s_nop 0
	v_min_f32_e32 v35, 0x7149f2ca, v10
	v_add_f32_e32 v10, 1.0, v35
	v_rcp_f32_e32 v37, v10
	s_nop 0
	v_fma_f32 v10, v90, v37, v122
	v_pk_mul_f32 v[34:35], v[34:35], v[36:37]
	v_log_f32_e32 v10, v10
	v_pk_mul_f32 v[34:35], v[90:91], v[34:35]
	v_mul_f32_e32 v11, 0x3f317217, v10
	v_fma_f32 v11, v10, s95, -v11
	v_fmac_f32_e32 v11, 0x3377d1cf, v10
	v_fmac_f32_e32 v11, 0x3f317217, v10
	v_mov_b32_e32 v10, v11
	v_add_f32_e32 v60, v54, v10
	v_mov_b32_e32 v10, v227
	v_mov_b32_e32 v11, v228
	s_waitcnt lgkmcnt(1)
	v_lshlrev_b32_e32 v10, 16, v10
	v_mul_f32_e32 v10, 0xbfb8aa3b, v10
	v_exp_f32_e32 v10, v10
	s_nop 0
	v_min_f32_e32 v30, 0x7149f2ca, v10
	v_add_f32_e32 v10, 1.0, v30
	v_rcp_f32_e32 v32, v10
	s_nop 0
	v_fma_f32 v10, v90, v32, v122
	v_log_f32_e32 v10, v10
	s_nop 0
	v_mul_f32_e32 v12, 0x3f317217, v10
	v_fma_f32 v12, v10, s95, -v12
	v_fmac_f32_e32 v12, 0x3377d1cf, v10
	v_fmac_f32_e32 v12, 0x3f317217, v10
	v_mov_b32_e32 v10, v12
	v_add_f32_e32 v52, v60, v10
	v_mov_b32_e32 v10, v229
	s_waitcnt lgkmcnt(0)
	v_lshlrev_b32_e32 v12, 16, v10
	v_mov_b32_e32 v10, v230
	s_waitcnt lgkmcnt(0)
	v_lshl_or_b32 v10, v10, 16, v11
	v_mul_f32_e32 v11, 0xbfb8aa3b, v12
	v_exp_f32_e32 v11, v11
	s_nop 0
	v_min_f32_e32 v31, 0x7149f2ca, v11
	v_add_f32_e32 v11, 1.0, v31
	v_rcp_f32_e32 v33, v11
	s_nop 0
	v_fma_f32 v11, v90, v33, v122
	v_pk_mul_f32 v[30:31], v[30:31], v[32:33]
	v_log_f32_e32 v11, v11
	v_pk_mul_f32 v[30:31], v[90:91], v[30:31]
	v_mul_f32_e32 v12, 0x3f317217, v11
	v_fma_f32 v12, v11, s95, -v12
	v_fmac_f32_e32 v12, 0x3377d1cf, v11
	v_fmac_f32_e32 v12, 0x3f317217, v11
	v_mov_b32_e32 v11, v12
	v_add_f32_e32 v59, v52, v11
	v_mov_b32_e32 v11, v231
	v_mov_b32_e32 v12, v232
	s_waitcnt lgkmcnt(1)
	v_lshlrev_b32_e32 v11, 16, v11
	v_mul_f32_e32 v11, 0xbfb8aa3b, v11
	v_exp_f32_e32 v11, v11
	s_nop 0
	v_min_f32_e32 v26, 0x7149f2ca, v11
	v_add_f32_e32 v11, 1.0, v26
	v_rcp_f32_e32 v28, v11
	s_nop 0
	v_fma_f32 v11, v90, v28, v122
	v_log_f32_e32 v11, v11
	s_nop 0
	v_mul_f32_e32 v13, 0x3f317217, v11
	v_fma_f32 v13, v11, s95, -v13
	v_fmac_f32_e32 v13, 0x3377d1cf, v11
	v_fmac_f32_e32 v13, 0x3f317217, v11
	v_mov_b32_e32 v11, v13
	v_add_f32_e32 v51, v59, v11
	v_mov_b32_e32 v11, v233
	s_waitcnt lgkmcnt(0)
	v_lshlrev_b32_e32 v13, 16, v11
	v_mov_b32_e32 v11, v234
	s_waitcnt lgkmcnt(0)
	v_lshl_or_b32 v11, v11, 16, v12
	v_mul_f32_e32 v12, 0xbfb8aa3b, v13
	v_exp_f32_e32 v12, v12
	s_nop 0
	v_min_f32_e32 v27, 0x7149f2ca, v12
	v_add_f32_e32 v12, 1.0, v27
	v_rcp_f32_e32 v29, v12
	s_nop 0
	v_fma_f32 v12, v90, v29, v122
	v_pk_mul_f32 v[26:27], v[26:27], v[28:29]
	v_log_f32_e32 v12, v12
	v_pk_mul_f32 v[26:27], v[90:91], v[26:27]
	v_mul_f32_e32 v13, 0x3f317217, v12
	v_fma_f32 v13, v12, s95, -v13
	v_fmac_f32_e32 v13, 0x3377d1cf, v12
	v_fmac_f32_e32 v13, 0x3f317217, v12
	v_mov_b32_e32 v12, v13
	v_add_f32_e32 v57, v51, v12
	v_mov_b32_e32 v12, v235
	v_mov_b32_e32 v13, v236
	s_waitcnt lgkmcnt(1)
	v_lshlrev_b32_e32 v12, 16, v12
	v_mul_f32_e32 v12, 0xbfb8aa3b, v12
	v_exp_f32_e32 v12, v12
	s_nop 0
	v_min_f32_e32 v22, 0x7149f2ca, v12
	v_add_f32_e32 v12, 1.0, v22
	v_rcp_f32_e32 v24, v12
	s_nop 0
	v_fma_f32 v12, v90, v24, v122
	v_log_f32_e32 v12, v12
	s_nop 0
	v_mul_f32_e32 v18, 0x3f317217, v12
	v_fma_f32 v18, v12, s95, -v18
	v_fmac_f32_e32 v18, 0x3377d1cf, v12
	v_fmac_f32_e32 v18, 0x3f317217, v12
	v_mov_b32_e32 v12, v18
	v_add_f32_e32 v50, v57, v12
	v_mov_b32_e32 v12, v237
	s_waitcnt lgkmcnt(0)
	v_lshlrev_b32_e32 v18, 16, v12
	v_mov_b32_e32 v12, v238
	s_waitcnt lgkmcnt(0)
	v_lshl_or_b32 v12, v12, 16, v13
	v_mul_f32_e32 v13, 0xbfb8aa3b, v18
	v_exp_f32_e32 v13, v13
	s_nop 0
	v_min_f32_e32 v23, 0x7149f2ca, v13
	v_add_f32_e32 v13, 1.0, v23
	v_rcp_f32_e32 v25, v13
	s_nop 0
	v_fma_f32 v13, v90, v25, v122
	v_pk_mul_f32 v[22:23], v[22:23], v[24:25]
	v_log_f32_e32 v13, v13
	v_pk_mul_f32 v[22:23], v[90:91], v[22:23]
	v_mul_f32_e32 v18, 0x3f317217, v13
	v_fma_f32 v18, v13, s95, -v18
	v_fmac_f32_e32 v18, 0x3377d1cf, v13
	v_fmac_f32_e32 v18, 0x3f317217, v13
	v_mov_b32_e32 v13, v18
	v_add_f32_e32 v55, v50, v13
	v_mov_b32_e32 v13, v239
	s_waitcnt lgkmcnt(0)
	v_lshlrev_b32_e32 v13, 16, v13
	v_mul_f32_e32 v13, 0xbfb8aa3b, v13
	v_exp_f32_e32 v13, v13
	s_nop 0
	v_min_f32_e32 v18, 0x7149f2ca, v13
	v_add_f32_e32 v13, 1.0, v18
	v_rcp_f32_e32 v20, v13
	s_nop 0
	v_fma_f32 v13, v90, v20, v122
	v_log_f32_e32 v13, v13
	s_nop 0
	v_mul_f32_e32 v21, 0x3f317217, v13
	v_fma_f32 v21, v13, s95, -v21
	v_fmac_f32_e32 v21, 0x3377d1cf, v13
	v_fmac_f32_e32 v21, 0x3f317217, v13
	v_mov_b32_e32 v13, v21
	v_add_f32_e32 v49, v55, v13
	v_mov_b32_e32 v13, v240
	s_waitcnt lgkmcnt(0)
	v_lshlrev_b32_e32 v21, 16, v13
	v_mov_b32_e32 v13, v241
	ds_read_u16 v63, v130
	ds_read_u16 v64, v131
	ds_read_u16 v65, v132
	ds_read_u16 v66, v133
	ds_read_u16 v68, v134
	ds_read_u16 v69, v135
	ds_read_u16 v67, v136
	ds_read_u16 v72, v137
	ds_read_u16 v70, v138
	ds_read_u16 v71, v139
	ds_read_u16 v73, v140
	ds_read_u16 v74, v141
	ds_read_u16 v76, v142
	ds_read_u16 v77, v143
	ds_read_u16 v75, v144
	ds_read_u16 v78, v145
	s_waitcnt lgkmcnt(14)
	v_lshlrev_b32_e32 v83, 16, v64
	v_lshlrev_b32_e32 v82, 16, v63
	s_waitcnt lgkmcnt(8)
	v_lshlrev_b32_e32 v41, 16, v72
	v_lshl_or_b32 v13, v13, 16, v19
	v_mul_f32_e32 v19, 0xbfb8aa3b, v21
	v_exp_f32_e32 v19, v19
	v_lshlrev_b32_e32 v40, 16, v67
	s_waitcnt lgkmcnt(6)
	v_lshlrev_b32_e32 v37, 16, v71
	v_lshlrev_b32_e32 v36, 16, v70
	v_min_f32_e32 v19, 0x7149f2ca, v19
	v_add_f32_e32 v21, 1.0, v19
	v_rcp_f32_e32 v21, v21
	s_waitcnt lgkmcnt(2)
	v_lshlrev_b32_e32 v29, 16, v77
	v_lshlrev_b32_e32 v28, 16, v76
	s_waitcnt lgkmcnt(0)
	v_lshlrev_b32_e32 v25, 16, v78
	v_fma_f32 v46, v90, v21, v122
	v_lshlrev_b32_e32 v24, 16, v75
	v_pk_mul_f32 v[18:19], v[18:19], v[20:21]
	v_log_f32_e32 v46, v46
	v_pk_mul_f32 v[18:19], v[90:91], v[18:19]
	v_mul_f32_e32 v47, 0x3f317217, v46
	v_fma_f32 v47, v46, s95, -v47
	v_fmac_f32_e32 v47, 0x3377d1cf, v46
	v_fmac_f32_e32 v47, 0x3f317217, v46
	v_mov_b32_e32 v46, v47
	v_add_f32_e32 v53, v49, v46
	ds_write_b32 v125, v53 offset:37632
	s_waitcnt lgkmcnt(0)
	s_barrier
; __device__ __forceinline__ unsigned pk2(float lo, float hi) { f32x2n v = {lo, hi}; bf16x2n b = __builtin_convertvector(v, bf16x2n); return __builtin_bit_cast(unsigned, b); }
; #define LAS __attribute__((address_space(3)))
; DI void hg_unit(LAS unsigned char* lds, const MixL& P, int pi) {
;     ...
;         { const float c0 = CUMQ[d], c1 = CUMQ[64 + d], c2 = CUMQ[128 + d], c3 = CUMQ[192 + d];
;           const float bref = c0 + c1, blast = bref + (c2 + c3);
;           const float pre = (tq == 0) ? 0.f : (tq == 1 ? c0 : (tq == 2 ? bref : bref + c2));
;           unsigned kt[8];
; #pragma unroll
;           for (int i = 0; i < 16; i += 2) { const float b0 = pre + cs[i], b1 = pre + cs[i + 1];
;               const unsigned qp = pk2(qv[i] * __expf(b0 - bref), qv[i + 1] * __expf(b1 - bref)), kp = pk2(kv[i] * __expf(bref - b0), kv[i + 1] * __expf(bref - b1));
;               *(LAS unsigned short*)(QE + (16 * tq + i) * LS + d * 2) = (unsigned short)(qp & 0xffffu); *(LAS unsigned short*)(QE + (16 * tq + i + 1) * LS + d * 2) = (unsigned short)(qp >> 16);
;               *(LAS unsigned short*)(KE + (16 * tq + i) * LS + d * 2) = (unsigned short)(kp & 0xffffu); *(LAS unsigned short*)(KE + (16 * tq + i + 1) * LS + d * 2) = (unsigned short)(kp >> 16);
;               kt[i >> 1] = kp; }
;           *(LAS u32x4*)(KET + d * LS + tq * 32) = (u32x4){kt[0], kt[1], kt[2], kt[3]}; *(LAS u32x4*)(KET + d * LS + tq * 32 + 16) = (u32x4){kt[4], kt[5], kt[6], kt[7]};
;           *(LAS u32x4*)(VT + d * LS + tq * 32) = (u32x4){vv[0], vv[1], vv[2], vv[3]}; *(LAS u32x4*)(VT + d * LS + tq * 32 + 16) = (u32x4){vv[4], vv[5], vv[6], vv[7]};
;           if (tq == 0) { EBREF[d] = __expf(bref); EBLR[d] = __expf(blast - bref); EBLAST[d] = __expf(blast); } }
	ds_read2st64_b32 v[80:81], v123 offset0:147 offset1:148
	ds_read2st64_b32 v[46:47], v123 offset0:149 offset1:150
	s_andn2_b64 vcc, exec, s[22:23]
	s_waitcnt lgkmcnt(1)
	v_add_f32_e32 v79, v80, v81
	s_waitcnt lgkmcnt(0)
	v_add_f32_e32 v81, v79, v46
	v_cndmask_b32_e64 v81, v81, v79, s[8:9]
	v_cndmask_b32_e64 v80, v81, v80, s[6:7]
	v_cndmask_b32_e64 v84, v80, 0, s[22:23]
	v_add_f32_e32 v9, v9, v84
	v_add_f32_e32 v48, v48, v84
	v_sub_f32_e32 v80, v9, v79
	v_sub_f32_e32 v81, v48, v79
	v_mul_f32_e32 v80, 0x3fb8aa3b, v80
	v_mul_f32_e32 v81, 0x3fb8aa3b, v81
	v_exp_f32_e32 v80, v80
	v_exp_f32_e32 v81, v81
	v_sub_f32_e32 v9, v79, v9
	v_mul_f32_e32 v9, 0x3fb8aa3b, v9
	v_add_f32_e32 v44, v61, v84
	v_pk_mul_f32 v[80:81], v[80:81], v[82:83]
	s_nop 0
	v_cvt_pk_bf16_f32 v63, v80, v81
	v_exp_f32_e32 v80, v9
	v_sub_f32_e32 v9, v79, v48
	v_mul_f32_e32 v9, 0x3fb8aa3b, v9
	v_exp_f32_e32 v81, v9
	v_add_f32_e32 v9, v58, v84
	v_sub_f32_e32 v16, v9, v79
	v_mul_f32_e32 v16, 0x3fb8aa3b, v16
	v_pk_mul_f32 v[14:15], v[14:15], v[80:81]
	v_exp_f32_e32 v16, v16
	v_cvt_pk_bf16_f32 v14, v14, v15
	v_add_f32_e32 v15, v62, v84
	v_sub_f32_e32 v17, v15, v79
	v_mul_f32_e32 v17, 0x3fb8aa3b, v17
	v_exp_f32_e32 v17, v17
	ds_write_b16 v146, v63
	ds_write_b16_d16_hi v146, v63 offset:144
	ds_write_b16 v146, v14 offset:9216
	ds_write_b16_d16_hi v146, v14 offset:9360
	v_lshlrev_b32_e32 v63, 16, v66
	v_lshlrev_b32_e32 v62, 16, v65
	v_sub_f32_e32 v9, v79, v9
	v_pk_mul_f32 v[16:17], v[16:17], v[62:63]
	v_mul_f32_e32 v9, 0x3fb8aa3b, v9
	v_cvt_pk_bf16_f32 v48, v16, v17
	v_exp_f32_e32 v16, v9
	v_sub_f32_e32 v9, v79, v15
	v_mul_f32_e32 v9, 0x3fb8aa3b, v9
	v_exp_f32_e32 v17, v9
	v_add_f32_e32 v9, v56, v84
	v_pk_mul_f32 v[16:17], v[42:43], v[16:17]
	s_nop 0
	v_cvt_pk_bf16_f32 v15, v16, v17
	v_sub_f32_e32 v16, v9, v79
	v_sub_f32_e32 v17, v44, v79
	v_mul_f32_e32 v16, 0x3fb8aa3b, v16
	v_mul_f32_e32 v17, 0x3fb8aa3b, v17
	v_exp_f32_e32 v16, v16
	v_exp_f32_e32 v17, v17
	v_lshlrev_b32_e32 v43, 16, v69
	v_lshlrev_b32_e32 v42, 16, v68
	v_sub_f32_e32 v9, v79, v9
	v_pk_mul_f32 v[16:17], v[16:17], v[42:43]
	v_mul_f32_e32 v9, 0x3fb8aa3b, v9
	v_cvt_pk_bf16_f32 v42, v16, v17
	v_exp_f32_e32 v16, v9
	v_sub_f32_e32 v9, v79, v44
	v_mul_f32_e32 v9, 0x3fb8aa3b, v9
	v_exp_f32_e32 v17, v9
	v_add_f32_e32 v9, v54, v84
	ds_write_b16 v146, v48 offset:288
	ds_write_b16_d16_hi v146, v48 offset:432
	ds_write_b16 v146, v15 offset:9504
	ds_write_b16_d16_hi v146, v15 offset:9648
	v_pk_mul_f32 v[16:17], v[38:39], v[16:17]
	s_nop 0
	v_cvt_pk_bf16_f32 v16, v16, v17
	v_add_f32_e32 v17, v60, v84
	v_sub_f32_e32 v38, v9, v79
	v_sub_f32_e32 v39, v17, v79
	v_mul_f32_e32 v38, 0x3fb8aa3b, v38
	v_mul_f32_e32 v39, 0x3fb8aa3b, v39
	v_exp_f32_e32 v38, v38
	v_exp_f32_e32 v39, v39
	v_sub_f32_e32 v9, v79, v9
	v_mul_f32_e32 v9, 0x3fb8aa3b, v9
	ds_write_b16 v146, v42 offset:576
	ds_write_b16_d16_hi v146, v42 offset:720
	ds_write_b16 v146, v16 offset:9792
	ds_write_b16_d16_hi v146, v16 offset:9936
	v_pk_mul_f32 v[38:39], v[38:39], v[40:41]
	s_nop 0
	v_cvt_pk_bf16_f32 v40, v38, v39
	v_exp_f32_e32 v38, v9
	v_sub_f32_e32 v9, v79, v17
	v_mul_f32_e32 v9, 0x3fb8aa3b, v9
	v_exp_f32_e32 v39, v9
	v_add_f32_e32 v9, v52, v84
	v_pk_mul_f32 v[34:35], v[34:35], v[38:39]
	v_add_f32_e32 v38, v59, v84
	v_cvt_pk_bf16_f32 v17, v34, v35
	v_sub_f32_e32 v34, v9, v79
	v_sub_f32_e32 v35, v38, v79
	v_mul_f32_e32 v34, 0x3fb8aa3b, v34
	v_mul_f32_e32 v35, 0x3fb8aa3b, v35
	v_exp_f32_e32 v34, v34
	v_exp_f32_e32 v35, v35
	v_sub_f32_e32 v9, v79, v9
	v_mul_f32_e32 v9, 0x3fb8aa3b, v9
	ds_write_b16 v146, v40 offset:864
	ds_write_b16_d16_hi v146, v40 offset:1008
	ds_write_b16 v146, v17 offset:10080
	ds_write_b16_d16_hi v146, v17 offset:10224
	v_pk_mul_f32 v[34:35], v[34:35], v[36:37]
	s_nop 0
	v_cvt_pk_bf16_f32 v36, v34, v35
	v_exp_f32_e32 v34, v9
	v_sub_f32_e32 v9, v79, v38
	v_mul_f32_e32 v9, 0x3fb8aa3b, v9
	v_exp_f32_e32 v35, v9
	v_add_f32_e32 v9, v51, v84
	v_sub_f32_e32 v32, v9, v79
	v_mul_f32_e32 v32, 0x3fb8aa3b, v32
	v_pk_mul_f32 v[30:31], v[30:31], v[34:35]
	v_exp_f32_e32 v32, v32
	v_cvt_pk_bf16_f32 v30, v30, v31
	v_add_f32_e32 v31, v57, v84
	v_sub_f32_e32 v33, v31, v79
	v_mul_f32_e32 v33, 0x3fb8aa3b, v33
	v_exp_f32_e32 v33, v33
	v_lshlrev_b32_e32 v35, 16, v74
	v_lshlrev_b32_e32 v34, 16, v73
	v_sub_f32_e32 v9, v79, v9
	v_pk_mul_f32 v[32:33], v[32:33], v[34:35]
	v_mul_f32_e32 v9, 0x3fb8aa3b, v9
	v_cvt_pk_bf16_f32 v34, v32, v33
	v_exp_f32_e32 v32, v9
	v_sub_f32_e32 v9, v79, v31
	v_mul_f32_e32 v9, 0x3fb8aa3b, v9
	v_exp_f32_e32 v33, v9
	v_add_f32_e32 v9, v50, v84
	ds_write_b16 v146, v36 offset:1152
	ds_write_b16_d16_hi v146, v36 offset:1296
	ds_write_b16 v146, v30 offset:10368
	ds_write_b16_d16_hi v146, v30 offset:10512
	v_pk_mul_f32 v[26:27], v[26:27], v[32:33]
	v_add_f32_e32 v32, v55, v84
	v_cvt_pk_bf16_f32 v31, v26, v27
	v_sub_f32_e32 v26, v9, v79
	v_sub_f32_e32 v27, v32, v79
	v_mul_f32_e32 v26, 0x3fb8aa3b, v26
	v_mul_f32_e32 v27, 0x3fb8aa3b, v27
	v_exp_f32_e32 v26, v26
	v_exp_f32_e32 v27, v27
	v_sub_f32_e32 v9, v79, v9
	v_mul_f32_e32 v9, 0x3fb8aa3b, v9
	ds_write_b16 v146, v34 offset:1440
	ds_write_b16_d16_hi v146, v34 offset:1584
	ds_write_b16 v146, v31 offset:10656
	ds_write_b16_d16_hi v146, v31 offset:10800
	v_pk_mul_f32 v[26:27], v[26:27], v[28:29]
	s_nop 0
	v_cvt_pk_bf16_f32 v28, v26, v27
	v_exp_f32_e32 v26, v9
	v_sub_f32_e32 v9, v79, v32
	v_mul_f32_e32 v9, 0x3fb8aa3b, v9
	v_exp_f32_e32 v27, v9
	v_add_f32_e32 v9, v49, v84
	v_pk_mul_f32 v[22:23], v[22:23], v[26:27]
	v_add_f32_e32 v26, v53, v84
	v_cvt_pk_bf16_f32 v32, v22, v23
	v_sub_f32_e32 v22, v9, v79
	v_sub_f32_e32 v23, v26, v79
	v_mul_f32_e32 v22, 0x3fb8aa3b, v22
	v_mul_f32_e32 v23, 0x3fb8aa3b, v23
	v_exp_f32_e32 v22, v22
	v_exp_f32_e32 v23, v23
	v_sub_f32_e32 v9, v79, v9
	v_mul_f32_e32 v9, 0x3fb8aa3b, v9
	ds_write_b16 v146, v28 offset:1728
	ds_write_b16_d16_hi v146, v28 offset:1872
	ds_write_b16 v146, v32 offset:10944
	ds_write_b16_d16_hi v146, v32 offset:11088
	v_pk_mul_f32 v[22:23], v[22:23], v[24:25]
	s_nop 0
	v_cvt_pk_bf16_f32 v24, v22, v23
	v_exp_f32_e32 v22, v9
	v_sub_f32_e32 v9, v79, v26
	v_mul_f32_e32 v9, 0x3fb8aa3b, v9
	v_exp_f32_e32 v23, v9
	v_add_u32_e32 v9, s52, v126
	v_pk_mul_f32 v[18:19], v[18:19], v[22:23]
	s_nop 0
	v_cvt_pk_bf16_f32 v33, v18, v19
	ds_write_b16 v146, v24 offset:2016
	ds_write_b16_d16_hi v146, v24 offset:2160
	ds_write_b16 v146, v33 offset:11232
	ds_write_b16_d16_hi v146, v33 offset:11376
	ds_write_b128 v9, v[14:17] offset:18432
	ds_write_b128 v9, v[30:33] offset:18448
	ds_write_b128 v9, v[4:7] offset:27648
	ds_write_b128 v9, v[10:13] offset:27664
	s_cbranch_vccnz .LBB0_526
	v_add_f32_e32 v4, v46, v47
	v_add_f32_e32 v4, v79, v4
	v_sub_f32_e32 v6, v4, v79
	v_mul_f32_e32 v5, 0x3fb8aa3b, v79
	v_mul_f32_e32 v6, 0x3fb8aa3b, v6
	v_exp_f32_e32 v5, v5
	v_exp_f32_e32 v6, v6
	v_mul_f32_e32 v4, 0x3fb8aa3b, v4
	v_exp_f32_e32 v4, v4
	ds_write2st64_b32 v147, v5, v6 offset0:144 offset1:145
	ds_write_b32 v147, v4 offset:37376
